# attention: unmasked/no-rescale path of both sub-tiles straight-line (masked variants, rescale and skip blocks out of line): about 11 fewer taken branches per key tile
# baseline (speedup 1.0000x reference)
.LBB0_509:
	s_or_b64 exec, exec, s[4:5]
	v_add_u32_e32 v65, s12, v190
	v_mov_b32_e32 v70, s33
	v_cmp_lt_i32_e32 vcc, 15, v65
	v_min_i32_e32 v64, 0x80f, v65
	s_and_b32 s89, 1, s64
	v_cndmask_b32_e32 v65, v179, v70, vcc
	v_add_u32_e32 v66, v65, v64
	v_ashrrev_i32_e32 v67, 31, v66
	v_lshlrev_b64 v[66:67], 14, v[66:67]
	v_lshl_add_u64 v[66:67], v[160:161], 0, v[66:67]
	v_add_co_u32_e32 v68, vcc, s65, v66
	v_ashrrev_i32_e32 v65, 31, v64
	s_nop 0
	v_addc_co_u32_e32 v69, vcc, 0, v67, vcc
	v_add_co_u32_e32 v66, vcc, s63, v66
	v_lshl_add_u64 v[64:65], v[64:65], 2, s[54:55]
	s_nop 0
	v_addc_co_u32_e32 v67, vcc, 0, v67, vcc
	global_load_dwordx4 v[130:133], v[68:69], off offset:2048
	global_load_dwordx4 v[116:119], v[66:67], off
	v_add_u32_e32 v67, s12, v189
	v_cmp_lt_i32_e32 vcc, 15, v67
	v_min_i32_e32 v66, 0x80f, v67
	s_cselect_b32 s4, 0, 0x8a00
	v_cndmask_b32_e32 v67, v179, v70, vcc
	v_add_u32_e32 v68, v67, v66
	v_ashrrev_i32_e32 v69, 31, v68
	v_lshlrev_b64 v[68:69], 14, v[68:69]
	v_lshl_add_u64 v[68:69], v[160:161], 0, v[68:69]
	v_add_co_u32_e32 v70, vcc, 0x2000, v68
	v_ashrrev_i32_e32 v67, 31, v66
	s_nop 0
	v_addc_co_u32_e32 v71, vcc, 0, v69, vcc
	global_load_dword v168, v[64:65], off
	global_load_dwordx4 v[120:123], v[70:71], off offset:2048
	v_add_co_u32_e32 v64, vcc, 0x3000, v68
	v_lshl_add_u64 v[66:67], v[66:67], 2, s[54:55]
	s_nop 0
	v_addc_co_u32_e32 v65, vcc, 0, v69, vcc
	global_load_dwordx4 v[124:127], v[64:65], off
	global_load_dword v166, v[66:67], off
	s_add_i32 s4, s4, 0
	v_add_u32_e32 v193, s4, v162
	v_add_u32_e32 v64, s4, v177
	v_add_u32_e32 v191, s4, v247
	s_add_i32 s4, s12, 32
	s_cmp_gt_i32 s4, s82
	s_cbranch_scc1 .LBB0_530
	v_add_u32_e32 v68, v193, v176
	ds_read_b128 v[64:67], v68
	ds_read_b128 v[134:137], v68 offset:32
	ds_read_b128 v[138:141], v68 offset:64
	ds_read_b128 v[142:145], v68 offset:96
	ds_read_b128 v[150:153], v68 offset:128
	ds_read_b128 v[170:173], v68 offset:160
	ds_read_b128 v[194:197], v68 offset:192
	ds_read_b128 v[198:201], v68 offset:224
	s_waitcnt lgkmcnt(7)
	v_mfma_f32_32x32x16_bf16 v[64:79], v[64:67], v[80:83], 0
	s_add_i32 s4, s12, 63
	s_cmp_le_i32 s4, s15
	s_cselect_b64 s[56:57], -1, 0
	s_cmp_gt_i32 s4, s15
	s_mov_b64 s[4:5], -1
	s_waitcnt lgkmcnt(6)
	v_mfma_f32_32x32x16_bf16 v[64:79], v[134:137], v[84:87], v[64:79]
	s_waitcnt lgkmcnt(5)
	v_mfma_f32_32x32x16_bf16 v[64:79], v[138:141], v[88:91], v[64:79]
	s_waitcnt lgkmcnt(4)
	v_mfma_f32_32x32x16_bf16 v[64:79], v[142:145], v[92:95], v[64:79]
	ds_read_b64_tr_b16 v[146:147], v191 offset:25600
	ds_read_b64_tr_b16 v[148:149], v191 offset:27648
	ds_read_b64_tr_b16 v[142:143], v191 offset:29696
	ds_read_b64_tr_b16 v[144:145], v191 offset:31744
	ds_read_b64_tr_b16 v[138:139], v191 offset:26112
	ds_read_b64_tr_b16 v[140:141], v191 offset:28160
	ds_read_b64_tr_b16 v[134:135], v191 offset:30208
	ds_read_b64_tr_b16 v[136:137], v191 offset:32256
	s_waitcnt lgkmcnt(11)
	v_mfma_f32_32x32x16_bf16 v[64:79], v[150:153], v[96:99], v[64:79]
	ds_read_b128 v[150:153], v193 offset:34944
	s_waitcnt lgkmcnt(11)
	v_mfma_f32_32x32x16_bf16 v[64:79], v[170:173], v[100:103], v[64:79]
	s_waitcnt lgkmcnt(0)
	v_xor_b32_e32 v173, 0x80000000, v152
	v_mfma_f32_32x32x16_bf16 v[64:79], v[194:197], v[104:107], v[64:79]
	v_mfma_f32_32x32x16_bf16 v[64:79], v[198:201], v[108:111], v[64:79]
	s_nop 11
	v_sub_f32_e32 v195, v64, v150
	s_cbranch_scc1 .LBB0_512
	v_mov_b32_e32 v170, v65
	v_mov_b32_e32 v171, v66
	v_xor_b32_e32 v172, 0x80000000, v151
	v_pk_add_f32 v[170:171], v[170:171], v[172:173]
	v_sub_f32_e32 v172, v67, v153
	v_max3_f32 v64, v195, s87, v170
	v_max3_f32 v196, v64, v171, v172
	ds_read_b128 v[64:67], v193 offset:34976
	s_waitcnt lgkmcnt(0)
	v_xor_b32_e32 v67, 0x80000000, v67
	v_xor_b32_e32 v66, 0x80000000, v66
	v_pk_add_f32 v[150:151], v[68:69], v[64:65] neg_lo:[0,1] neg_hi:[0,1]
	v_pk_add_f32 v[152:153], v[70:71], v[66:67]
	v_max3_f32 v173, v196, v150, v151
	v_max3_f32 v173, v173, v152, v153
	ds_read_b128 v[64:67], v193 offset:35008
	s_waitcnt lgkmcnt(0)
	v_xor_b32_e32 v67, 0x80000000, v67
	v_xor_b32_e32 v66, 0x80000000, v66
	v_pk_add_f32 v[68:69], v[72:73], v[64:65] neg_lo:[0,1] neg_hi:[0,1]
	v_pk_add_f32 v[70:71], v[74:75], v[66:67]
	v_max3_f32 v196, v173, v68, v69
	v_max3_f32 v196, v196, v70, v71
	ds_read_b128 v[64:67], v193 offset:35040
	s_waitcnt lgkmcnt(0)
	v_xor_b32_e32 v75, 0x80000000, v67
	v_xor_b32_e32 v74, 0x80000000, v66
	v_pk_add_f32 v[72:73], v[76:77], v[64:65] neg_lo:[0,1] neg_hi:[0,1]
	v_pk_add_f32 v[66:67], v[78:79], v[74:75]
	v_max3_f32 v173, v196, v72, v73
	v_max3_f32 v173, v173, v66, v67
.LBB0_526:
	v_mov_b32_e32 v64, v173
	s_nop 1
	v_permlane32_swap_b32_e32 v173, v64
	v_max_f32_e32 v64, v64, v64
	v_max_f32_e32 v65, v173, v173
	v_max_f32_e32 v64, v65, v64
	v_max_f32_e32 v65, v192, v192
	v_max_f32_e32 v194, v65, v64
	v_cmp_neq_f32_e64 s[4:5], s87, v194
	v_cmp_gt_f32_e32 vcc, v64, v192
	s_nop 0
	v_cndmask_b32_e64 v64, 0, v194, s[4:5]
	s_cbranch_vccnz .LattA_resc
.LBB0_528:
	v_sub_f32_e32 v65, v195, v64
	v_exp_f32_e32 v173, v65
	v_sub_f32_e32 v65, v170, v64
	v_exp_f32_e32 v170, v65
	v_sub_f32_e32 v65, v171, v64
	v_exp_f32_e32 v171, v65
	v_sub_f32_e32 v65, v172, v64
	v_exp_f32_e32 v172, v65
	v_sub_f32_e32 v65, v150, v64
	v_exp_f32_e32 v150, v65
	v_sub_f32_e32 v65, v151, v64
	v_exp_f32_e32 v151, v65
	v_sub_f32_e32 v65, v152, v64
	v_exp_f32_e32 v152, v65
	v_sub_f32_e32 v65, v153, v64
	v_exp_f32_e32 v153, v65
	v_sub_f32_e32 v65, v68, v64
	v_exp_f32_e32 v192, v65
	v_sub_f32_e32 v65, v69, v64
	v_exp_f32_e32 v195, v65
	v_sub_f32_e32 v65, v70, v64
	v_exp_f32_e32 v196, v65
	v_sub_f32_e32 v65, v71, v64
	v_cvt_pk_bf16_f32 v68, v173, v170
	v_cvt_pk_bf16_f32 v69, v171, v172
	v_cvt_pk_bf16_f32 v70, v150, v151
	v_cvt_pk_bf16_f32 v71, v152, v153
	v_exp_f32_e32 v197, v65
	v_sub_f32_e32 v65, v72, v64
	v_mfma_f32_32x32x16_bf16 v[32:47], v[138:141], v[68:71], v[32:47]
	v_exp_f32_e32 v198, v65
	v_sub_f32_e32 v65, v73, v64
	v_exp_f32_e32 v199, v65
	v_sub_f32_e32 v65, v66, v64
	v_sub_f32_e32 v64, v67, v64
	ds_read_b64_tr_b16 v[72:73], v191 offset:26624
	v_cvt_pk_bf16_f32 v66, v198, v199
	v_mfma_f32_32x32x16_bf16 v[48:63], v[146:149], v[68:71], v[48:63]
	v_exp_f32_e32 v146, v65
	v_exp_f32_e32 v147, v64
	v_cvt_pk_bf16_f32 v64, v192, v195
	v_cvt_pk_bf16_f32 v65, v196, v197
	v_cvt_pk_bf16_f32 v67, v146, v147
	s_nop 1
	v_mfma_f32_32x32x16_bf16 v[32:47], v[134:137], v[64:67], v[32:47]
	ds_read_b64_tr_b16 v[74:75], v191 offset:28672
	ds_read_b64_tr_b16 v[76:77], v191 offset:30720
	ds_read_b64_tr_b16 v[134:135], v191 offset:31232
	ds_read_b64_tr_b16 v[140:141], v191 offset:29184
	ds_read_b64_tr_b16 v[138:139], v191 offset:27136
	ds_read_b64_tr_b16 v[136:137], v191 offset:33280
	ds_read_b64_tr_b16 v[78:79], v191 offset:32768
	s_waitcnt lgkmcnt(6)
	v_mfma_f32_32x32x16_bf16 v[16:31], v[72:75], v[68:71], v[16:31]
	v_add_f32_e32 v72, 0, v173
	v_add_f32_e32 v72, v170, v72
	v_add_f32_e32 v72, v171, v72
	v_add_f32_e32 v72, v172, v72
	v_add_f32_e32 v72, v150, v72
	v_add_f32_e32 v72, v151, v72
	v_add_f32_e32 v72, v152, v72
	s_waitcnt lgkmcnt(2)
	v_mfma_f32_32x32x16_bf16 v[0:15], v[138:141], v[68:71], v[0:15]
	v_add_f32_e32 v72, v153, v72
	v_add_f32_e32 v72, v192, v72
	v_add_f32_e32 v72, v195, v72
	v_add_f32_e32 v68, v196, v72
	v_add_f32_e32 v68, v197, v68
	v_add_f32_e32 v68, v198, v68
	v_add_f32_e32 v68, v199, v68
	v_mfma_f32_32x32x16_bf16 v[48:63], v[142:145], v[64:67], v[48:63]
	v_add_f32_e32 v68, v146, v68
	v_add_f32_e32 v68, v147, v68
	v_add_f32_e32 v167, v68, v167
	s_waitcnt lgkmcnt(0)
	v_mfma_f32_32x32x16_bf16 v[16:31], v[76:79], v[64:67], v[16:31]
	v_mfma_f32_32x32x16_bf16 v[0:15], v[134:137], v[64:67], v[0:15]
	s_cmp_gt_i32 s12, s82
	s_cbranch_scc1 .LBB0_529
.LBB0_531:
	v_add_u32_e32 v68, v193, v169
	ds_read_b128 v[64:67], v68
	ds_read_b128 v[134:137], v68 offset:32
	ds_read_b128 v[138:141], v68 offset:64
	ds_read_b128 v[142:145], v68 offset:96
	ds_read_b128 v[150:153], v68 offset:128
	ds_read_b128 v[170:173], v68 offset:160
	ds_read_b128 v[196:199], v68 offset:192
	ds_read_b128 v[200:203], v68 offset:224
	s_waitcnt lgkmcnt(7)
	v_mfma_f32_32x32x16_bf16 v[64:79], v[64:67], v[80:83], 0
	s_add_i32 s4, s12, 31
	s_cmp_le_i32 s4, s15
	s_cselect_b64 s[56:57], -1, 0
	s_cmp_gt_i32 s4, s15
	s_mov_b64 s[4:5], -1
	s_waitcnt lgkmcnt(6)
	v_mfma_f32_32x32x16_bf16 v[64:79], v[134:137], v[84:87], v[64:79]
	s_waitcnt lgkmcnt(5)
	v_mfma_f32_32x32x16_bf16 v[64:79], v[138:141], v[88:91], v[64:79]
	s_waitcnt lgkmcnt(4)
	v_mfma_f32_32x32x16_bf16 v[64:79], v[142:145], v[92:95], v[64:79]
	ds_read_b64_tr_b16 v[146:147], v191 offset:17408
	ds_read_b64_tr_b16 v[148:149], v191 offset:19456
	ds_read_b64_tr_b16 v[142:143], v191 offset:21504
	ds_read_b64_tr_b16 v[144:145], v191 offset:23552
	ds_read_b64_tr_b16 v[138:139], v191 offset:17920
	ds_read_b64_tr_b16 v[140:141], v191 offset:19968
	ds_read_b64_tr_b16 v[134:135], v191 offset:22016
	ds_read_b64_tr_b16 v[136:137], v191 offset:24064
	s_waitcnt lgkmcnt(11)
	v_mfma_f32_32x32x16_bf16 v[64:79], v[150:153], v[96:99], v[64:79]
	ds_read_b128 v[150:153], v193 offset:34816
	s_waitcnt lgkmcnt(11)
	v_mfma_f32_32x32x16_bf16 v[64:79], v[170:173], v[100:103], v[64:79]
	s_waitcnt lgkmcnt(0)
	v_xor_b32_e32 v173, 0x80000000, v152
	v_mfma_f32_32x32x16_bf16 v[64:79], v[196:199], v[104:107], v[64:79]
	v_mfma_f32_32x32x16_bf16 v[64:79], v[200:203], v[108:111], v[64:79]
	s_nop 11
	v_sub_f32_e32 v195, v64, v150
	s_cbranch_scc1 .LBB0_533
	v_mov_b32_e32 v170, v65
	v_mov_b32_e32 v171, v66
	v_xor_b32_e32 v172, 0x80000000, v151
	v_pk_add_f32 v[170:171], v[170:171], v[172:173]
	v_sub_f32_e32 v172, v67, v153
	v_max3_f32 v64, v195, s87, v170
	v_max3_f32 v196, v64, v171, v172
	ds_read_b128 v[64:67], v193 offset:34848
	s_waitcnt lgkmcnt(0)
	v_xor_b32_e32 v67, 0x80000000, v67
	v_xor_b32_e32 v66, 0x80000000, v66
	v_pk_add_f32 v[150:151], v[68:69], v[64:65] neg_lo:[0,1] neg_hi:[0,1]
	v_pk_add_f32 v[152:153], v[70:71], v[66:67]
	v_max3_f32 v173, v196, v150, v151
	v_max3_f32 v173, v173, v152, v153
	ds_read_b128 v[64:67], v193 offset:34880
	s_waitcnt lgkmcnt(0)
	v_xor_b32_e32 v67, 0x80000000, v67
	v_xor_b32_e32 v66, 0x80000000, v66
	v_pk_add_f32 v[68:69], v[72:73], v[64:65] neg_lo:[0,1] neg_hi:[0,1]
	v_pk_add_f32 v[70:71], v[74:75], v[66:67]
	v_max3_f32 v196, v173, v68, v69
	v_max3_f32 v196, v196, v70, v71
	ds_read_b128 v[64:67], v193 offset:34912
	s_waitcnt lgkmcnt(0)
	v_xor_b32_e32 v75, 0x80000000, v67
	v_xor_b32_e32 v74, 0x80000000, v66
	v_pk_add_f32 v[72:73], v[76:77], v[64:65] neg_lo:[0,1] neg_hi:[0,1]
	v_pk_add_f32 v[66:67], v[78:79], v[74:75]
	v_max3_f32 v173, v196, v72, v73
	v_max3_f32 v173, v173, v66, v67
.LBB0_547:
	v_mov_b32_e32 v64, v173
	s_nop 1
	v_permlane32_swap_b32_e32 v173, v64
	v_max_f32_e32 v64, v64, v64
	v_max_f32_e32 v65, v173, v173
	v_max_f32_e32 v64, v65, v64
	v_max_f32_e32 v65, v194, v194
	v_max_f32_e32 v192, v65, v64
	v_cmp_neq_f32_e64 s[4:5], s87, v192
	v_cmp_gt_f32_e32 vcc, v64, v194
	s_nop 0
	v_cndmask_b32_e64 v64, 0, v192, s[4:5]
	s_cbranch_vccnz .LattB_resc

.LBB0_550:
	s_cmp_eq_u32 s89, 1
	s_cselect_b32 s4, 0x8a00, 0
	s_add_i32 s56, s4, 0
	s_and_saveexec_b64 s[4:5], s[0:1]
	s_cbranch_execz .LBB0_506
	v_add_u32_e32 v64, s56, v187
	s_waitcnt vmcnt(6)
	ds_write_b128 v64, v[112:115] offset:34816
	s_branch .LBB0_506
.LBB0_512:
	s_andn2_b64 vcc, exec, s[4:5]
	v_add3_u32 v194, v159, s12, 32
	s_cbranch_vccnz .LBB0_514
	v_cmp_le_i32_e32 vcc, v194, v158
	v_xor_b32_e32 v153, 0x80000000, v153
	v_sub_f32_e32 v64, v65, v151
	v_cndmask_b32_e32 v195, v180, v195, vcc
	v_cmp_lt_i32_e32 vcc, v194, v158
	v_or_b32_e32 v151, 3, v194
	v_mov_b32_e32 v152, v173
	v_cndmask_b32_e32 v170, v180, v64, vcc
	v_or_b32_e32 v171, 2, v194
	v_pk_add_f32 v[64:65], v[66:67], v[152:153]
	v_cmp_le_i32_e32 vcc, v151, v155
	v_max3_f32 v150, v195, s87, v170
	s_nop 0
	v_cndmask_b32_e32 v172, v180, v65, vcc
	v_cmp_le_i32_e32 vcc, v171, v158
	s_nop 1
	v_cndmask_b32_e32 v171, v180, v64, vcc
	v_max3_f32 v196, v150, v171, v172

.LBB0_524:
	s_andn2_b64 vcc, exec, s[56:57]
	s_cbranch_vccnz .LBB0_526
	v_or_b32_e32 v66, 25, v194
	v_or_b32_e32 v67, 24, v194
	v_pk_add_f32 v[64:65], v[76:77], v[64:65] neg_lo:[0,1] neg_hi:[0,1]
	v_cmp_le_i32_e32 vcc, v66, v155
	v_or_b32_e32 v66, 27, v194
	v_or_b32_e32 v77, 26, v194
	v_cndmask_b32_e32 v73, v180, v65, vcc
	v_cmp_le_i32_e32 vcc, v67, v158
	s_nop 1
	v_cndmask_b32_e32 v72, v180, v64, vcc
	v_pk_add_f32 v[64:65], v[78:79], v[74:75]
	v_cmp_le_i32_e32 vcc, v66, v155
	v_max3_f32 v76, v196, v72, v73
	s_nop 0
	v_cndmask_b32_e32 v67, v180, v65, vcc
	v_cmp_le_i32_e32 vcc, v77, v158
	s_nop 1
	v_cndmask_b32_e32 v66, v180, v64, vcc
	v_max3_f32 v173, v76, v66, v67
	s_branch .LBB0_526
.LattA_resc:
	v_sub_f32_e32 v65, v192, v64
	v_exp_f32_e32 v74, v65
	s_nop 0
	v_pk_mul_f32 v[62:63], v[62:63], v[74:75] op_sel_hi:[1,0]
	v_pk_mul_f32 v[60:61], v[60:61], v[74:75] op_sel_hi:[1,0]
	v_pk_mul_f32 v[58:59], v[58:59], v[74:75] op_sel_hi:[1,0]
	v_pk_mul_f32 v[56:57], v[56:57], v[74:75] op_sel_hi:[1,0]
	v_pk_mul_f32 v[54:55], v[54:55], v[74:75] op_sel_hi:[1,0]
	v_pk_mul_f32 v[52:53], v[52:53], v[74:75] op_sel_hi:[1,0]
	v_pk_mul_f32 v[50:51], v[50:51], v[74:75] op_sel_hi:[1,0]
	v_pk_mul_f32 v[48:49], v[48:49], v[74:75] op_sel_hi:[1,0]
	v_pk_mul_f32 v[46:47], v[46:47], v[74:75] op_sel_hi:[1,0]
	v_pk_mul_f32 v[44:45], v[44:45], v[74:75] op_sel_hi:[1,0]
	v_pk_mul_f32 v[42:43], v[42:43], v[74:75] op_sel_hi:[1,0]
	v_pk_mul_f32 v[40:41], v[40:41], v[74:75] op_sel_hi:[1,0]
	v_pk_mul_f32 v[38:39], v[38:39], v[74:75] op_sel_hi:[1,0]
	v_pk_mul_f32 v[36:37], v[36:37], v[74:75] op_sel_hi:[1,0]
	v_pk_mul_f32 v[34:35], v[34:35], v[74:75] op_sel_hi:[1,0]
	v_pk_mul_f32 v[32:33], v[32:33], v[74:75] op_sel_hi:[1,0]
	v_pk_mul_f32 v[30:31], v[30:31], v[74:75] op_sel_hi:[1,0]
	v_pk_mul_f32 v[28:29], v[28:29], v[74:75] op_sel_hi:[1,0]
	v_pk_mul_f32 v[26:27], v[26:27], v[74:75] op_sel_hi:[1,0]
	v_pk_mul_f32 v[24:25], v[24:25], v[74:75] op_sel_hi:[1,0]
	v_pk_mul_f32 v[22:23], v[22:23], v[74:75] op_sel_hi:[1,0]
	v_pk_mul_f32 v[20:21], v[20:21], v[74:75] op_sel_hi:[1,0]
	v_pk_mul_f32 v[18:19], v[18:19], v[74:75] op_sel_hi:[1,0]
	v_pk_mul_f32 v[16:17], v[16:17], v[74:75] op_sel_hi:[1,0]
	v_pk_mul_f32 v[14:15], v[14:15], v[74:75] op_sel_hi:[1,0]
	v_pk_mul_f32 v[12:13], v[12:13], v[74:75] op_sel_hi:[1,0]
	v_pk_mul_f32 v[10:11], v[10:11], v[74:75] op_sel_hi:[1,0]
	v_pk_mul_f32 v[8:9], v[8:9], v[74:75] op_sel_hi:[1,0]
	v_pk_mul_f32 v[6:7], v[6:7], v[74:75] op_sel_hi:[1,0]
	v_pk_mul_f32 v[4:5], v[4:5], v[74:75] op_sel_hi:[1,0]
	v_pk_mul_f32 v[2:3], v[2:3], v[74:75] op_sel_hi:[1,0]
	v_pk_mul_f32 v[0:1], v[0:1], v[74:75] op_sel_hi:[1,0]
	v_mul_f32_e32 v167, v167, v74
	s_branch .LBB0_528

.LBB0_530:
	v_mov_b32_e32 v194, v192
	s_cmp_gt_i32 s12, s82
	s_cbranch_scc1 .LBB0_529
	s_branch .LBB0_531

.LBB0_545:
	s_andn2_b64 vcc, exec, s[56:57]
	s_cbranch_vccnz .LBB0_547
	v_or_b32_e32 v66, 25, v192
	v_or_b32_e32 v67, 24, v192
	v_pk_add_f32 v[64:65], v[76:77], v[64:65] neg_lo:[0,1] neg_hi:[0,1]
	v_cmp_le_i32_e32 vcc, v66, v155
	v_or_b32_e32 v66, 27, v192
	v_or_b32_e32 v77, 26, v192
	v_cndmask_b32_e32 v73, v180, v65, vcc
	v_cmp_le_i32_e32 vcc, v67, v158
	s_nop 1
	v_cndmask_b32_e32 v72, v180, v64, vcc
	v_pk_add_f32 v[64:65], v[78:79], v[74:75]
	v_cmp_le_i32_e32 vcc, v66, v155
	v_max3_f32 v76, v196, v72, v73
	s_nop 0
	v_cndmask_b32_e32 v67, v180, v65, vcc
	v_cmp_le_i32_e32 vcc, v77, v158
	s_nop 1
	v_cndmask_b32_e32 v66, v180, v64, vcc
	v_max3_f32 v173, v76, v66, v67
	s_branch .LBB0_547
.LattB_resc:
	v_sub_f32_e32 v65, v194, v64
	v_exp_f32_e32 v74, v65
	s_nop 0
	v_pk_mul_f32 v[62:63], v[62:63], v[74:75] op_sel_hi:[1,0]
	v_pk_mul_f32 v[60:61], v[60:61], v[74:75] op_sel_hi:[1,0]
	v_pk_mul_f32 v[58:59], v[58:59], v[74:75] op_sel_hi:[1,0]
	v_pk_mul_f32 v[56:57], v[56:57], v[74:75] op_sel_hi:[1,0]
	v_pk_mul_f32 v[54:55], v[54:55], v[74:75] op_sel_hi:[1,0]
	v_pk_mul_f32 v[52:53], v[52:53], v[74:75] op_sel_hi:[1,0]
	v_pk_mul_f32 v[50:51], v[50:51], v[74:75] op_sel_hi:[1,0]
	v_pk_mul_f32 v[48:49], v[48:49], v[74:75] op_sel_hi:[1,0]
	v_pk_mul_f32 v[46:47], v[46:47], v[74:75] op_sel_hi:[1,0]
	v_pk_mul_f32 v[44:45], v[44:45], v[74:75] op_sel_hi:[1,0]
	v_pk_mul_f32 v[42:43], v[42:43], v[74:75] op_sel_hi:[1,0]
	v_pk_mul_f32 v[40:41], v[40:41], v[74:75] op_sel_hi:[1,0]
	v_pk_mul_f32 v[38:39], v[38:39], v[74:75] op_sel_hi:[1,0]
	v_pk_mul_f32 v[36:37], v[36:37], v[74:75] op_sel_hi:[1,0]
	v_pk_mul_f32 v[34:35], v[34:35], v[74:75] op_sel_hi:[1,0]
	v_pk_mul_f32 v[32:33], v[32:33], v[74:75] op_sel_hi:[1,0]
	v_pk_mul_f32 v[30:31], v[30:31], v[74:75] op_sel_hi:[1,0]
	v_pk_mul_f32 v[28:29], v[28:29], v[74:75] op_sel_hi:[1,0]
	v_pk_mul_f32 v[26:27], v[26:27], v[74:75] op_sel_hi:[1,0]
	v_pk_mul_f32 v[24:25], v[24:25], v[74:75] op_sel_hi:[1,0]
	v_pk_mul_f32 v[22:23], v[22:23], v[74:75] op_sel_hi:[1,0]
	v_pk_mul_f32 v[20:21], v[20:21], v[74:75] op_sel_hi:[1,0]
	v_pk_mul_f32 v[18:19], v[18:19], v[74:75] op_sel_hi:[1,0]
	v_pk_mul_f32 v[16:17], v[16:17], v[74:75] op_sel_hi:[1,0]
	v_pk_mul_f32 v[14:15], v[14:15], v[74:75] op_sel_hi:[1,0]
	v_pk_mul_f32 v[12:13], v[12:13], v[74:75] op_sel_hi:[1,0]
	v_pk_mul_f32 v[10:11], v[10:11], v[74:75] op_sel_hi:[1,0]
	v_pk_mul_f32 v[8:9], v[8:9], v[74:75] op_sel_hi:[1,0]
	v_pk_mul_f32 v[6:7], v[6:7], v[74:75] op_sel_hi:[1,0]
	v_pk_mul_f32 v[4:5], v[4:5], v[74:75] op_sel_hi:[1,0]
	v_pk_mul_f32 v[2:3], v[2:3], v[74:75] op_sel_hi:[1,0]
	v_pk_mul_f32 v[0:1], v[0:1], v[74:75] op_sel_hi:[1,0]
	v_mul_f32_e32 v167, v167, v74
	s_branch .LBB0_549
